# stack6 + P5 row loop waits relaxed: next-row loads overlap compute (single wait at latch)
# speedup vs baseline: 1.0046x; 1.0046x over previous
.LBB0_722:
	s_or_b64 exec, exec, s[0:1]
	s_ashr_i32 s0, s14, 6
	v_readlane_b32 s1, v233, 20
	s_add_i32 s14, s0, s1
	s_cmpk_gt_i32 s14, 0x3fff
	s_cbranch_scc1 .LBB0_731
	s_add_u32 s4, s92, 0x50000
	s_addc_u32 s5, s93, 0
	s_ashr_i32 s15, s14, 31
	s_lshl_b64 s[0:1], s[14:15], 12
	s_add_u32 s24, s6, s0
	s_addc_u32 s25, s7, s1
	s_add_u32 s26, s12, s0
	s_addc_u32 s27, s13, s1
	s_lshl_b64 s[68:69], s[14:15], 2
	s_add_u32 s28, s38, s68
	v_mov_b32_e32 v37, 0
	s_addc_u32 s29, s39, s69
	v_lshlrev_b32_e32 v36, 3, v32
	global_load_dword v142, v37, s[28:29]
	global_load_dwordx2 v[38:39], v36, s[24:25] nt
	global_load_dwordx2 v[40:41], v36, s[24:25] offset:512 nt
	global_load_dwordx2 v[42:43], v36, s[24:25] offset:1024 nt
	global_load_dwordx2 v[44:45], v36, s[24:25] offset:1536 nt
	global_load_dwordx2 v[46:47], v36, s[26:27] nt
	global_load_dwordx2 v[48:49], v36, s[26:27] offset:512 nt
	global_load_dwordx2 v[50:51], v36, s[26:27] offset:1024 nt
	global_load_dwordx2 v[52:53], v36, s[26:27] offset:1536 nt
	global_load_dwordx2 v[54:55], v36, s[24:25] offset:2048 nt
	global_load_dwordx2 v[56:57], v36, s[24:25] offset:2560 nt
	global_load_dwordx2 v[58:59], v36, s[24:25] offset:3072 nt
	global_load_dwordx2 v[60:61], v36, s[24:25] offset:3584 nt
	global_load_dwordx2 v[62:63], v36, s[26:27] offset:2048 nt
	global_load_dwordx2 v[64:65], v36, s[26:27] offset:2560 nt
	global_load_dwordx2 v[66:67], v36, s[26:27] offset:3072 nt
	global_load_dwordx2 v[68:69], v36, s[26:27] offset:3584 nt
	s_add_u32 s33, s68, 0x40000
	v_lshl_add_u32 v33, v32, 4, 0
	s_addc_u32 s88, s69, 0
	s_ashr_i32 s97, s96, 31
	v_lshl_add_u64 v[70:71], s[6:7], 0, v[36:37]
	v_lshl_add_u64 v[72:73], s[12:13], 0, v[36:37]
	s_mov_b32 s15, 0
	v_cmp_eq_u32_e64 s[44:45], 0, v32
	v_add_u32_e32 v34, 0x10000, v33
	v_add_u32_e32 v108, 0x10400, v33
	v_add_u32_e32 v109, 0x10800, v33
	v_add_u32_e32 v110, 0x10c00, v33
	v_add_u32_e32 v111, 0x11000, v33
	v_add_u32_e32 v112, 0x11400, v33
	v_add_u32_e32 v113, 0x11800, v33
	v_add_u32_e32 v114, 0x11c00, v33
	v_add_u32_e32 v115, 0x12000, v33
	v_add_u32_e32 v116, 0x12400, v33
	v_add_u32_e32 v117, 0x12800, v33
	v_add_u32_e32 v118, 0x12c00, v33
	v_add_u32_e32 v119, 0x13000, v33
	v_add_u32_e32 v120, 0x13400, v33
	v_add_u32_e32 v121, 0x13800, v33
	v_add_u32_e32 v122, 0x13c00, v33
	v_add_u32_e32 v123, 0x14000, v33
	v_add_u32_e32 v124, 0x14400, v33
	v_add_u32_e32 v125, 0x14800, v33
	v_add_u32_e32 v126, 0x14c00, v33
	v_add_u32_e32 v127, 0x15000, v33
	v_add_u32_e32 v128, 0x15400, v33
	v_add_u32_e32 v129, 0x15800, v33
	v_add_u32_e32 v130, 0x15c00, v33
	v_add_u32_e32 v131, 0x16000, v33
	v_add_u32_e32 v132, 0x16400, v33
	v_add_u32_e32 v133, 0x16800, v33
	v_add_u32_e32 v134, 0x16c00, v33
	v_add_u32_e32 v135, 0x17000, v33
	v_add_u32_e32 v136, 0x17400, v33
	v_add_u32_e32 v137, 0x17800, v33
	v_add_u32_e32 v138, 0x17c00, v33
	v_cmp_eq_u32_e64 s[46:47], 1, v32
	v_cmp_eq_u32_e64 s[48:49], 2, v32
	v_cmp_eq_u32_e64 s[50:51], 3, v32
	v_cmp_eq_u32_e64 s[52:53], 4, v32
	v_cmp_eq_u32_e64 s[54:55], 5, v32
	v_cmp_eq_u32_e64 s[56:57], 6, v32
	v_cmp_eq_u32_e64 s[58:59], 7, v32
	v_cmp_eq_u32_e64 s[60:61], 8, v32
	v_cmp_eq_u32_e64 s[62:63], 9, v32
	v_cmp_eq_u32_e64 s[64:65], 10, v32
	v_cmp_eq_u32_e64 s[66:67], 11, v32
	s_lshl_b64 s[84:85], s[96:97], 2
	v_or_b32_e32 v74, s0, v36
	v_mov_b32_e32 v75, s1
	s_lshl_b64 s[86:87], s[96:97], 12
	v_readlane_b32 s97, v232, 51
	v_mov_b32_e32 v36, 0x358637bd
	s_mov_b32 s89, 0xf800000
	v_mov_b32_e32 v139, 0x260
	v_mov_b32_e32 v140, 0x41b17218
	s_waitcnt vmcnt(0)
	v_mov_b32_e32 v141, v142
	s_branch .LBB0_725
.LBB0_724:
	s_or_b64 exec, exec, s[82:83]
	s_waitcnt vmcnt(8)
	s_add_u32 s33, s33, s84
	v_cndmask_b32_e64 v46, v46, v76, s[68:69]
	v_cndmask_b32_e64 v47, v47, v77, s[68:69]
	v_cndmask_b32_e64 v48, v48, v80, s[68:69]
	v_cndmask_b32_e64 v49, v49, v81, s[68:69]
	v_cndmask_b32_e64 v50, v50, v82, s[68:69]
	v_cndmask_b32_e64 v51, v51, v83, s[68:69]
	v_cndmask_b32_e64 v52, v52, v86, s[68:69]
	v_cndmask_b32_e64 v53, v53, v87, s[68:69]
	v_cndmask_b32_e64 v62, v62, v92, s[68:69]
	v_cndmask_b32_e64 v63, v63, v93, s[68:69]
	v_cndmask_b32_e64 v64, v64, v96, s[68:69]
	v_cndmask_b32_e64 v65, v65, v97, s[68:69]
	v_cndmask_b32_e64 v66, v66, v98, s[68:69]
	v_cndmask_b32_e64 v67, v67, v99, s[68:69]
	v_cndmask_b32_e64 v68, v68, v102, s[68:69]
	v_cndmask_b32_e64 v69, v69, v103, s[68:69]
	v_cndmask_b32_e64 v38, v38, v78, s[68:69]
	v_cndmask_b32_e64 v39, v39, v79, s[68:69]
	v_cndmask_b32_e64 v40, v40, v84, s[68:69]
	v_cndmask_b32_e64 v41, v41, v85, s[68:69]
	v_cndmask_b32_e64 v42, v42, v88, s[68:69]
	v_cndmask_b32_e64 v43, v43, v89, s[68:69]
	v_cndmask_b32_e64 v44, v44, v90, s[68:69]
	v_cndmask_b32_e64 v45, v45, v91, s[68:69]
	v_cndmask_b32_e64 v54, v54, v94, s[68:69]
	v_cndmask_b32_e64 v55, v55, v95, s[68:69]
	v_cndmask_b32_e64 v56, v56, v100, s[68:69]
	v_cndmask_b32_e64 v57, v57, v101, s[68:69]
	v_cndmask_b32_e64 v58, v58, v104, s[68:69]
	v_cndmask_b32_e64 v59, v59, v105, s[68:69]
	v_cndmask_b32_e64 v60, v60, v106, s[68:69]
	v_cndmask_b32_e64 v61, v61, v107, s[68:69]
	s_addc_u32 s88, s88, s85
	v_lshl_add_u64 v[74:75], v[74:75], 0, s[86:87]
	s_and_b64 vcc, exec, s[80:81]
	v_mov_b32_e32 v142, v141
	s_mov_b32 s14, s76
	s_cbranch_vccnz .LBB0_731

.LBB0_727:
	v_fmamk_f32 v142, v142, 0x3a000000, v36
	v_cmp_gt_f32_e32 vcc, s89, v142
	v_mul_f32_e32 v143, 0x4f800000, v142
	v_and_b32_e32 v148, 0xffff0000, v47
	v_cndmask_b32_e32 v142, v142, v143, vcc
	v_sqrt_f32_e32 v143, v142
	v_and_b32_e32 v151, 0xffff0000, v49
	v_lshlrev_b32_e32 v153, 16, v51
	v_and_b32_e32 v155, 0xffff0000, v51
	v_add_u32_e32 v144, -1, v143
	v_fma_f32 v145, -v144, v143, v142
	v_cmp_ge_f32_e64 s[0:1], 0, v145
	v_add_u32_e32 v145, 1, v143
	v_lshlrev_b32_e32 v157, 16, v53
	v_cndmask_b32_e64 v144, v143, v144, s[0:1]
	v_fma_f32 v143, -v145, v143, v142
	v_cmp_lt_f32_e64 s[0:1], 0, v143
	v_and_b32_e32 v159, 0xffff0000, v53
	v_lshlrev_b32_e32 v161, 16, v63
	v_cndmask_b32_e64 v143, v144, v145, s[0:1]
	v_mul_f32_e32 v144, 0x37800000, v143
	v_cndmask_b32_e32 v143, v143, v144, vcc
	v_cmp_class_f32_e32 vcc, v142, v139
	v_and_b32_e32 v163, 0xffff0000, v63
	v_lshlrev_b32_e32 v166, 16, v65
	v_cndmask_b32_e32 v142, v143, v142, vcc
	v_div_scale_f32 v143, s[0:1], v142, v142, 1.0
	v_rcp_f32_e32 v144, v143
	s_mov_b32 s0, 0x4d00000
	v_and_b32_e32 v168, 0xffff0000, v65
	v_lshlrev_b32_e32 v170, 16, v67
	v_fma_f32 v145, -v143, v144, 1.0
	v_fmac_f32_e32 v144, v145, v144
	v_div_scale_f32 v145, vcc, 1.0, v142, 1.0
	v_mul_f32_e32 v146, v145, v144
	v_fma_f32 v147, -v143, v146, v145
	v_fmac_f32_e32 v146, v147, v144
	v_fma_f32 v143, -v143, v146, v145
	v_div_fmas_f32 v143, v143, v144, v146
	v_div_fixup_f32 v165, v143, v142, 1.0
	v_lshlrev_b32_e32 v143, 16, v46
	v_lshlrev_b32_e32 v142, 16, v38
	v_mul_f32_e32 v143, v165, v143
	v_and_b32_e32 v144, 0xffff0000, v46
	v_fmac_f32_e32 v142, v143, v0
	v_and_b32_e32 v143, 0xffff0000, v38
	v_mul_f32_e32 v144, v165, v144
	v_lshlrev_b32_e32 v145, 16, v47
	v_fmac_f32_e32 v143, v144, v1
	v_lshlrev_b32_e32 v144, 16, v39
	v_mul_f32_e32 v145, v165, v145
	v_fmac_f32_e32 v144, v145, v2
	v_and_b32_e32 v145, 0xffff0000, v39
	v_mul_f32_e32 v148, v165, v148
	v_fmac_f32_e32 v145, v148, v3
	v_lshl_add_u64 v[146:147], s[92:93], 0, v[74:75]
	v_mul_f32_e32 v148, v143, v143
	v_mul_f32_e32 v149, v145, v145
	v_fmac_f32_e32 v148, v142, v142
	v_fmac_f32_e32 v149, v144, v144
	v_add_co_u32_e32 v176, vcc, s0, v146
	v_add_f32_e32 v150, v148, v149
	v_cvt_pk_bf16_f32 v148, v142, v143
	s_nop 0
	v_addc_co_u32_e32 v177, vcc, 0, v147, vcc
	v_lshlrev_b32_e32 v147, 16, v48
	v_cvt_pk_bf16_f32 v149, v144, v145
	global_store_dwordx2 v[176:177], v[148:149], off
	v_lshlrev_b32_e32 v146, 16, v40
	v_mul_f32_e32 v147, v165, v147
	v_and_b32_e32 v148, 0xffff0000, v48
	v_fmac_f32_e32 v146, v147, v4
	v_and_b32_e32 v147, 0xffff0000, v40
	v_mul_f32_e32 v148, v165, v148
	v_lshlrev_b32_e32 v149, 16, v49
	v_fmac_f32_e32 v147, v148, v5
	v_lshlrev_b32_e32 v148, 16, v41
	v_mul_f32_e32 v149, v165, v149
	v_fmac_f32_e32 v148, v149, v6
	v_and_b32_e32 v149, 0xffff0000, v41
	v_mul_f32_e32 v151, v165, v151
	v_fmac_f32_e32 v149, v151, v7
	v_mul_f32_e32 v151, v147, v147
	v_mul_f32_e32 v152, v149, v149
	v_fmac_f32_e32 v151, v146, v146
	v_fmac_f32_e32 v152, v148, v148
	v_add_f32_e32 v151, v151, v152
	v_add_f32_e32 v154, v150, v151
	v_cvt_pk_bf16_f32 v150, v146, v147
	v_cvt_pk_bf16_f32 v151, v148, v149
	global_store_dwordx2 v[176:177], v[150:151], off offset:512
	v_lshlrev_b32_e32 v151, 16, v50
	v_lshlrev_b32_e32 v150, 16, v42
	v_mul_f32_e32 v151, v165, v151
	v_and_b32_e32 v152, 0xffff0000, v50
	v_fmac_f32_e32 v150, v151, v8
	v_and_b32_e32 v151, 0xffff0000, v42
	v_mul_f32_e32 v152, v165, v152
	v_fmac_f32_e32 v151, v152, v9
	v_lshlrev_b32_e32 v152, 16, v43
	v_mul_f32_e32 v153, v165, v153
	v_fmac_f32_e32 v152, v153, v10
	v_and_b32_e32 v153, 0xffff0000, v43
	v_mul_f32_e32 v155, v165, v155
	v_fmac_f32_e32 v153, v155, v11
	v_mul_f32_e32 v155, v151, v151
	v_mul_f32_e32 v156, v153, v153
	v_fmac_f32_e32 v155, v150, v150
	v_fmac_f32_e32 v156, v152, v152
	v_add_f32_e32 v155, v155, v156
	v_add_f32_e32 v158, v154, v155
	v_cvt_pk_bf16_f32 v154, v150, v151
	v_cvt_pk_bf16_f32 v155, v152, v153
	global_store_dwordx2 v[176:177], v[154:155], off offset:1024
	v_lshlrev_b32_e32 v155, 16, v52
	v_lshlrev_b32_e32 v154, 16, v44
	v_mul_f32_e32 v155, v165, v155
	v_and_b32_e32 v156, 0xffff0000, v52
	v_fmac_f32_e32 v154, v155, v12
	v_and_b32_e32 v155, 0xffff0000, v44
	v_mul_f32_e32 v156, v165, v156
	v_fmac_f32_e32 v155, v156, v13
	v_lshlrev_b32_e32 v156, 16, v45
	v_mul_f32_e32 v157, v165, v157
	v_fmac_f32_e32 v156, v157, v14
	v_and_b32_e32 v157, 0xffff0000, v45
	v_mul_f32_e32 v159, v165, v159
	v_fmac_f32_e32 v157, v159, v15
	v_mul_f32_e32 v159, v155, v155
	v_mul_f32_e32 v160, v157, v157
	v_fmac_f32_e32 v159, v154, v154
	v_fmac_f32_e32 v160, v156, v156
	v_add_f32_e32 v159, v159, v160
	v_add_f32_e32 v162, v158, v159
	v_cvt_pk_bf16_f32 v158, v154, v155
	v_cvt_pk_bf16_f32 v159, v156, v157
	global_store_dwordx2 v[176:177], v[158:159], off offset:1536
	v_lshlrev_b32_e32 v159, 16, v62
	v_lshlrev_b32_e32 v158, 16, v54
	v_mul_f32_e32 v159, v165, v159
	v_and_b32_e32 v160, 0xffff0000, v62
	v_fmac_f32_e32 v158, v159, v16
	v_and_b32_e32 v159, 0xffff0000, v54
	v_mul_f32_e32 v160, v165, v160
	v_fmac_f32_e32 v159, v160, v17
	v_lshlrev_b32_e32 v160, 16, v55
	v_mul_f32_e32 v161, v165, v161
	v_fmac_f32_e32 v160, v161, v18
	v_and_b32_e32 v161, 0xffff0000, v55
	v_mul_f32_e32 v163, v165, v163
	v_fmac_f32_e32 v161, v163, v19
	v_mul_f32_e32 v163, v159, v159
	v_mul_f32_e32 v164, v161, v161
	v_fmac_f32_e32 v163, v158, v158
	v_fmac_f32_e32 v164, v160, v160
	v_add_f32_e32 v163, v163, v164
	v_add_f32_e32 v167, v162, v163
	v_cvt_pk_bf16_f32 v162, v158, v159
	v_cvt_pk_bf16_f32 v163, v160, v161
	global_store_dwordx2 v[176:177], v[162:163], off offset:2048
	v_lshlrev_b32_e32 v163, 16, v64
	v_lshlrev_b32_e32 v162, 16, v56
	v_mul_f32_e32 v163, v165, v163
	v_and_b32_e32 v164, 0xffff0000, v64
	v_fmac_f32_e32 v162, v163, v20
	v_and_b32_e32 v163, 0xffff0000, v56
	v_mul_f32_e32 v164, v165, v164
	v_fmac_f32_e32 v163, v164, v21
	v_lshlrev_b32_e32 v164, 16, v57
	v_mul_f32_e32 v166, v165, v166
	v_fmac_f32_e32 v164, v166, v22
	v_and_b32_e32 v166, 0xffff0000, v57
	v_mul_f32_e32 v168, v165, v168
	v_fmac_f32_e32 v166, v168, v23
	v_mul_f32_e32 v168, v163, v163
	v_mul_f32_e32 v169, v166, v166
	v_fmac_f32_e32 v168, v162, v162
	v_fmac_f32_e32 v169, v164, v164
	v_add_f32_e32 v168, v168, v169
	v_add_f32_e32 v171, v167, v168
	v_cvt_pk_bf16_f32 v168, v162, v163
	v_cvt_pk_bf16_f32 v169, v164, v166
	global_store_dwordx2 v[176:177], v[168:169], off offset:2560
	v_lshlrev_b32_e32 v168, 16, v66
	v_lshlrev_b32_e32 v167, 16, v58
	v_mul_f32_e32 v168, v165, v168
	v_and_b32_e32 v169, 0xffff0000, v66
	v_fmac_f32_e32 v167, v168, v24
	v_and_b32_e32 v168, 0xffff0000, v58
	v_mul_f32_e32 v169, v165, v169
	v_fmac_f32_e32 v168, v169, v25
	v_lshlrev_b32_e32 v169, 16, v59
	v_mul_f32_e32 v170, v165, v170
	v_and_b32_e32 v172, 0xffff0000, v67
	v_fmac_f32_e32 v169, v170, v26
	v_and_b32_e32 v170, 0xffff0000, v59
	v_mul_f32_e32 v172, v165, v172
	v_fmac_f32_e32 v170, v172, v27
	v_mul_f32_e32 v172, v168, v168
	v_mul_f32_e32 v173, v170, v170
	v_fmac_f32_e32 v172, v167, v167
	v_fmac_f32_e32 v173, v169, v169
	v_add_f32_e32 v172, v172, v173
	v_add_f32_e32 v175, v171, v172
	v_cvt_pk_bf16_f32 v172, v167, v168
	v_cvt_pk_bf16_f32 v173, v169, v170
	global_store_dwordx2 v[176:177], v[172:173], off offset:3072
	v_lshlrev_b32_e32 v172, 16, v68
	v_lshlrev_b32_e32 v171, 16, v60
	v_mul_f32_e32 v172, v165, v172
	v_and_b32_e32 v173, 0xffff0000, v68
	v_fmac_f32_e32 v171, v172, v28
	v_and_b32_e32 v172, 0xffff0000, v60
	v_mul_f32_e32 v173, v165, v173
	v_lshlrev_b32_e32 v174, 16, v69
	v_fmac_f32_e32 v172, v173, v29
	v_lshlrev_b32_e32 v173, 16, v61
	v_mul_f32_e32 v174, v165, v174
	v_and_b32_e32 v178, 0xffff0000, v69
	v_fmac_f32_e32 v173, v174, v30
	v_and_b32_e32 v174, 0xffff0000, v61
	v_mul_f32_e32 v165, v165, v178
	v_fmac_f32_e32 v174, v165, v31
	v_mul_f32_e32 v165, v172, v172
	v_mul_f32_e32 v178, v174, v174
	v_fmac_f32_e32 v165, v171, v171
	v_fmac_f32_e32 v178, v173, v173
	v_add_f32_e32 v165, v165, v178
	v_add_f32_e32 v165, v175, v165
	v_cvt_pk_bf16_f32 v178, v171, v172
	v_cvt_pk_bf16_f32 v179, v173, v174
	global_store_dwordx2 v[176:177], v[178:179], off offset:3584
	s_nop 0
	v_add_f32_dpp v165, v165, v165 quad_perm:[1,0,3,2] row_mask:0xf bank_mask:0xf bound_ctrl:1
	s_nop 1
	v_add_f32_dpp v165, v165, v165 quad_perm:[2,3,0,1] row_mask:0xf bank_mask:0xf bound_ctrl:1
	s_nop 1
	v_add_f32_dpp v165, v165, v165 row_ror:4 row_mask:0xf bank_mask:0xf bound_ctrl:1
	s_nop 1
	v_add_f32_dpp v165, v165, v165 row_ror:8 row_mask:0xf bank_mask:0xf bound_ctrl:1
	v_mov_b32_e32 v175, v165
	s_nop 1
	v_permlane16_swap_b32_e32 v165, v175
	v_add_f32_e32 v165, v165, v175
	v_mov_b32_e32 v175, v165
	s_nop 1
	v_permlane32_swap_b32_e32 v165, v175
	v_add_f32_e32 v165, v165, v175
	v_fmamk_f32 v165, v165, 0x3a000000, v36
	v_cmp_gt_f32_e32 vcc, s89, v165
	v_mul_f32_e32 v175, 0x4f800000, v165
	s_nop 0
	v_cndmask_b32_e32 v165, v165, v175, vcc
	v_sqrt_f32_e32 v175, v165
	s_nop 0
	v_add_u32_e32 v176, -1, v175
	v_fma_f32 v177, -v176, v175, v165
	v_cmp_ge_f32_e64 s[0:1], 0, v177
	v_add_u32_e32 v177, 1, v175
	s_nop 0
	v_cndmask_b32_e64 v176, v175, v176, s[0:1]
	v_fma_f32 v175, -v177, v175, v165
	v_cmp_lt_f32_e64 s[0:1], 0, v175
	s_nop 1
	v_cndmask_b32_e64 v175, v176, v177, s[0:1]
	v_mul_f32_e32 v176, 0x37800000, v175
	v_cndmask_b32_e32 v175, v175, v176, vcc
	v_cmp_class_f32_e32 vcc, v165, v139
	s_nop 1
	v_cndmask_b32_e32 v165, v175, v165, vcc
	v_div_scale_f32 v175, s[0:1], v165, v165, 1.0
	v_rcp_f32_e32 v176, v175
	s_nop 0
	v_fma_f32 v177, -v175, v176, 1.0
	v_fmac_f32_e32 v176, v177, v176
	v_div_scale_f32 v177, vcc, 1.0, v165, 1.0
	v_mul_f32_e32 v178, v177, v176
	v_fma_f32 v179, -v175, v178, v177
	v_fmac_f32_e32 v178, v179, v176
	v_fma_f32 v175, -v175, v178, v177
	v_div_fmas_f32 v175, v175, v176, v178
	v_div_fixup_f32 v165, v175, v165, 1.0
	s_and_saveexec_b64 s[0:1], s[44:45]
	s_cbranch_execz .LBB0_729
	s_add_u32 s24, s92, s33
	s_addc_u32 s25, s93, s88
	global_store_dword v37, v165, s[24:25]
